# P3 step loop: wave 4 issues the k-row sumsq load before the row DMAs and waits vmcnt(2) (not vmcnt(0)); plus earlier edits
# baseline (speedup 1.0000x reference)
; #define LDS_WAIT() asm volatile("s_waitcnt lgkmcnt(0)" ::: "memory")
; #define VM_WAIT() asm volatile("s_waitcnt vmcnt(0)" ::: "memory")
; __global__ void __launch_bounds__(NWAVES * 64, 2) fwd(Args a) {
;     ...
;             for (int st = 0; st < 16; ++st) {
;                 if (wave < 4 && st > 0) asm volatile("s_waitcnt vmcnt(2)" ::: "memory"); else VM_WAIT();
;                 LDS_WAIT(); __builtin_amdgcn_s_barrier(); asm volatile("" ::: "memory");
;                 const int r = r0 + st, rs = min(max(r - 4, 0), rows - 8);
;                 if (st < 15) { const int rsn = min(max(r + 1 - 4, 0), rows - 8); if (rsn != rs) STAGE_ROW(rsn + 7); }
.LBB0_266:
	s_add_i32 s86, s42, s40
	s_max_i32 s28, s86, 4
	s_add_i32 s28, s28, -4
	s_waitcnt lgkmcnt(0)
	s_barrier
	s_min_i32 s41, s28, s84
	s_cmpk_lg_i32 s87, 0x3c0
	s_cselect_b64 s[56:57], -1, 0
	s_cmpk_eq_i32 s87, 0x3c0
	s_cbranch_scc1 .LBB0_270
	s_max_i32 s28, s86, 3
	s_add_i32 s28, s28, -3
	s_min_i32 s28, s28, s84
	s_cmp_eq_u32 s28, s41
	s_cbranch_scc1 .LBB0_270
	s_add_i32 s28, s28, 7
	s_mul_hi_u32 s43, s28, 0x38e38e39
	s_lshr_b32 s43, s43, 1
	s_mul_i32 s43, s43, 9
	s_sub_i32 s43, s28, s43
	s_lshl_b32 s28, s28, 6
	s_cmp_eq_u32 s88, 4
	s_cbranch_scc0 .Lrk2_skip
	v_lshl_add_u64 v[248:249], s[28:29], 2, v[142:143]
	global_load_dword v240, v[248:249], off
.Lrk2_skip:
	v_add_u32_e32 v34, s28, v193
	v_ashrrev_i32_e32 v35, 31, v34
	v_lshlrev_b64 v[34:35], 12, v[34:35]
	v_lshl_add_u64 v[34:35], v[4:5], 0, v[34:35]
	s_lshl_b32 s70, s43, 13
	v_lshl_add_u64 v[36:37], v[34:35], 0, s[18:19]
	s_add_i32 m0, s95, s70
	v_lshl_add_u64 v[34:35], v[34:35], 0, s[20:21]
	global_load_lds_dwordx4 v[36:37], off
	s_add_i32 m0, s96, s70
	s_and_b64 vcc, exec, s[12:13]
	global_load_lds_dwordx4 v[34:35], off
	s_cbranch_vccnz .LBB0_270
	s_waitcnt vmcnt(2)
	v_fmamk_f32 v2, v240, 0x3c800000, v191
	v_mul_f32_e32 v34, 0x4b800000, v2
	v_cmp_gt_f32_e32 vcc, s14, v2
	s_nop 1
	v_cndmask_b32_e32 v2, v2, v34, vcc
	v_rsq_f32_e32 v2, v2
	s_nop 0
	v_mul_f32_e32 v34, 0x45800000, v2
	v_cndmask_b32_e32 v2, v2, v34, vcc
	v_mul_f32_e32 v2, 0x3fb8aa3b, v2
	v_lshl_add_u32 v34, s43, 8, v172
	ds_write_b32 v34, v2
